# attention task epilogues: bf16 conversions write straight into the store quads (16 v_mov per task removed), on top of v105
# speedup vs baseline: 1.0072x; 1.0003x over previous
; __device__ __forceinline__ unsigned pk2(float lo, float hi) { f32x2 v = {lo, hi}; bf16x2_t b = __builtin_convertvector(v, bf16x2_t); return __builtin_bit_cast(unsigned, b); }
; __device__ __forceinline__ void attn_task(const AttnP& P, LAS unsigned char* lds, int b, int hd, int qq, int c, float shift, int lane_in) {
;     ...
;     const float rz = __builtin_amdgcn_rcpf(zacc[0]);
;     float ss = 0.f;
; #pragma unroll
;     for (int e = 0; e < 16; ++e) { o0[e] *= rz; o1[e] *= rz; ss += o0[e] * o0[e] + o1[e] * o1[e]; }
;     ss = xor32_sum(ss);
;     const size_t tok = (size_t)b * SEQ + c + 16 * (iq0 + q);
;     if (h == 0) P.ssqA[tok * 8 + hd] = ss;
;     bf16_t* orow = P.MIX + tok * DM + hd * 64;
; #pragma unroll
;     for (int e4 = 0; e4 < 4; ++e4) {
;         const int d0 = 8 * e4 + 4 * h;
;         u32x2 w0, w1;
;         w0.x = pk2(o0[4 * e4], o0[4 * e4 + 1]); w0.y = pk2(o0[4 * e4 + 2], o0[4 * e4 + 3]);
;         w1.x = pk2(o1[4 * e4], o1[4 * e4 + 1]); w1.y = pk2(o1[4 * e4 + 2], o1[4 * e4 + 3]);
;         *(u32x2*)(orow + d0) = w0; *(u32x2*)(orow + 32 + d0) = w1;
;     }
.LBB0_168:
	s_or_b64 exec, exec, s[0:1]
	v_readlane_b32 s0, v243, 20
	v_lshlrev_b64 v[34:35], 11, v[190:191]
	v_readlane_b32 s1, v243, 21
	v_lshlrev_b32_e32 v36, 2, v223
	v_ashrrev_i32_e32 v37, 31, v36
	v_lshl_add_u64 v[34:35], s[0:1], 0, v[34:35]
	v_lshl_add_u64 v[34:35], v[34:35], 0, s[58:59]
	v_cvt_pk_bf16_f32 v128, v4, v5
	v_cvt_pk_bf16_f32 v129, v10, v11
	v_cvt_pk_bf16_f32 v136, v2, v3
	v_cvt_pk_bf16_f32 v137, v6, v7
	v_lshl_add_u64 v[6:7], v[36:37], 1, v[34:35]
	v_bfe_u32 v144, v0, 5, 1
	v_lshlrev_b32_e32 v144, 3, v144
	v_mov_b32_e32 v145, 0
	v_lshl_add_u64 v[146:147], v[6:7], 0, v[144:145]
	v_cvt_pk_bf16_f32 v130, v12, v13
	v_cvt_pk_bf16_f32 v131, v16, v17
	v_cvt_pk_bf16_f32 v138, v8, v9
	v_cvt_pk_bf16_f32 v139, v14, v15
	s_nop 1
	v_permlane32_swap_b32_e32 v128, v130
	v_permlane32_swap_b32_e32 v129, v131
	global_store_dwordx4 v[146:147], v[128:131], off
	s_nop 1
	v_permlane32_swap_b32_e32 v136, v138
	v_permlane32_swap_b32_e32 v137, v139
	global_store_dwordx4 v[146:147], v[136:139], off offset:64
	v_cvt_pk_bf16_f32 v132, v20, v21
	v_cvt_pk_bf16_f32 v133, v24, v25
	v_cvt_pk_bf16_f32 v140, v18, v19
	v_cvt_pk_bf16_f32 v141, v22, v23
	s_add_i32 s97, s97, s3
	v_cvt_pk_bf16_f32 v134, v28, v29
	v_cvt_pk_bf16_f32 v135, v32, v33
	v_cvt_pk_bf16_f32 v142, v26, v27
	v_cvt_pk_bf16_f32 v143, v30, v31
	s_cmpk_gt_i32 s97, 0xff
	s_mov_b32 s30, 0x41f00000
	s_movk_i32 s31, 0x90
	s_movk_i32 s36, 0xfec0
	s_nop 1
	v_permlane32_swap_b32_e32 v132, v134
	v_permlane32_swap_b32_e32 v133, v135
	global_store_dwordx4 v[146:147], v[132:135], off offset:32
	s_nop 1
	v_permlane32_swap_b32_e32 v140, v142
	v_permlane32_swap_b32_e32 v141, v143
	global_store_dwordx4 v[146:147], v[140:143], off offset:96
	s_cbranch_scc1 .LBB0_535

; #define LAS __attribute__((address_space(3)))
; __device__ __forceinline__ unsigned pk2(float lo, float hi) { f32x2 v = {lo, hi}; bf16x2_t b = __builtin_convertvector(v, bf16x2_t); return __builtin_bit_cast(unsigned, b); }
; __device__ __forceinline__ int next_tile(int tt, int R0) { while (tt < 26 && !tile_valid(tt, R0)) ++tt; return tt; }
; __device__ __forceinline__ void attn_task(const AttnP& P, LAS unsigned char* lds, int b, int hd, int qq, int c, float shift, int lane_in) {
;     ...
;     const int hb = b * 8 + hd, q = lane & 31, h = lane >> 5, R0 = 4 * qq, iq0 = 32 * qq;
;     bf16x8 qf[4];
;     { const bf16_t* qp = P.Q + ((size_t)(hb * 16 + c) * 128 + iq0 + q) * 64 + 8 * h;
; #pragma unroll
;       for (int kk = 0; kk < 4; ++kk) qf[kk] = *(const bf16x8*)(qp + 16 * kk); }
;     bf16x8 gk[4];
;     int gi = next_tile(0, R0);
;     if (gi < 10) attn_load_k(P, lds, hb, gi, c, R0, lane, gk);
;     unsigned long long Hp[2], Hn[2], Bp[2], Bn[2], mT0[2], mT3[2], mAp[2], mAn[2], mLp, mLn;
;     { const LAS unsigned long long* T = (const LAS unsigned long long*)(lds + LDS_ATAB + lane * 144);
;       Hp[0] = T[0]; Hp[1] = T[1]; Hn[0] = T[2]; Hn[1] = T[3]; Bp[0] = T[4]; Bp[1] = T[5]; Bn[0] = T[6]; Bn[1] = T[7];
;       mT0[0] = T[8]; mT0[1] = T[9]; mT3[0] = T[10]; mT3[1] = T[11]; mAp[0] = T[12]; mAp[1] = T[13]; mAn[0] = T[14]; mAn[1] = T[15]; mLp = T[16]; mLn = T[17]; }
;     f32x16 o0 = {}, o1 = {}, zacc = {};
;     bf16x8 ones = {0x3F80, 0x3F80, 0x3F80, 0x3F80, 0x3F80, 0x3F80, 0x3F80, 0x3F80}; asm volatile("" : "+v"(ones));
;     int li = 10, ph = 0;
;     ...
;     const size_t tok = (size_t)b * SEQ + c + 16 * (iq0 + q);
;     if (h == 0) P.ssqA[tok * 8 + hd] = ss;
;     bf16_t* orow = P.MIX + tok * DM + hd * 64;
; #pragma unroll
;     for (int e4 = 0; e4 < 4; ++e4) {
;         const int d0 = 8 * e4 + 4 * h;
;         u32x2 w0, w1;
;         w0.x = pk2(o0[4 * e4], o0[4 * e4 + 1]); w0.y = pk2(o0[4 * e4 + 2], o0[4 * e4 + 3]);
;         w1.x = pk2(o1[4 * e4], o1[4 * e4 + 1]); w1.y = pk2(o1[4 * e4 + 2], o1[4 * e4 + 3]);
;         *(u32x2*)(orow + d0) = w0; *(u32x2*)(orow + 32 + d0) = w1;
;     }
.LBB0_249:
	s_or_b64 exec, exec, s[0:1]
	v_readlane_b32 s0, v243, 20
	v_lshlrev_b64 v[48:49], 11, v[190:191]
	v_readlane_b32 s1, v243, 21
	s_lshl_b32 s58, s98, 7
	v_lshlrev_b32_e32 v52, 2, v17
	v_lshl_add_u64 v[48:49], s[0:1], 0, v[48:49]
	v_lshl_add_u64 v[48:49], v[48:49], 0, s[58:59]
	v_ashrrev_i32_e32 v53, 31, v52
	v_cvt_pk_bf16_f32 v128, v50, v51
	v_cvt_pk_bf16_f32 v129, v34, v35
	v_cvt_pk_bf16_f32 v136, v18, v19
	v_cvt_pk_bf16_f32 v137, v20, v21
	v_lshl_add_u64 v[20:21], v[52:53], 1, v[48:49]
	v_bfe_u32 v144, v0, 5, 1
	v_lshlrev_b32_e32 v144, 3, v144
	v_mov_b32_e32 v145, 0
	v_lshl_add_u64 v[146:147], v[20:21], 0, v[144:145]
	v_cvt_pk_bf16_f32 v130, v36, v37
	v_cvt_pk_bf16_f32 v131, v38, v39
	v_cvt_pk_bf16_f32 v138, v22, v23
	v_cvt_pk_bf16_f32 v139, v24, v25
	s_nop 1
	v_permlane32_swap_b32_e32 v128, v130
	v_permlane32_swap_b32_e32 v129, v131
	global_store_dwordx4 v[146:147], v[128:131], off
	s_nop 1
	v_permlane32_swap_b32_e32 v136, v138
	v_permlane32_swap_b32_e32 v137, v139
	global_store_dwordx4 v[146:147], v[136:139], off offset:64
	v_cvt_pk_bf16_f32 v132, v40, v41
	v_cvt_pk_bf16_f32 v133, v42, v43
	v_cvt_pk_bf16_f32 v140, v26, v27
	v_cvt_pk_bf16_f32 v141, v28, v29
	v_cvt_pk_bf16_f32 v134, v44, v45
	v_cvt_pk_bf16_f32 v135, v46, v47
	v_mov_b32_e32 v229, v201
	s_add_i32 s58, s99, s64
	v_cvt_pk_bf16_f32 v142, v30, v31
	v_cvt_pk_bf16_f32 v143, v32, v33
	s_nop 1
	v_permlane32_swap_b32_e32 v132, v134
	v_permlane32_swap_b32_e32 v133, v135
	global_store_dwordx4 v[146:147], v[132:135], off offset:32
	s_nop 1
	v_permlane32_swap_b32_e32 v140, v142
	v_permlane32_swap_b32_e32 v141, v143
	global_store_dwordx4 v[146:147], v[140:143], off offset:96
	s_lshl_b64 s[26:27], s[58:59], 7
	v_and_b32_e32 v230, 31, v229
	v_ashrrev_i32_e32 v228, 5, v229
	v_or_b32_e32 v17, s26, v230
	v_mov_b32_e32 v19, s27
	v_or_b32_e32 v18, s13, v17
	v_lshlrev_b32_e32 v20, 3, v228
	v_lshlrev_b64 v[18:19], 7, v[18:19]
	v_ashrrev_i32_e32 v21, 31, v20
	v_lshl_add_u64 v[18:19], s[46:47], 0, v[18:19]
	v_lshlrev_b64 v[20:21], 1, v[20:21]
	v_lshl_add_u64 v[18:19], v[18:19], 0, v[20:21]
	global_load_dwordx4 v[86:89], v[18:19], off
	global_load_dwordx4 v[90:93], v[18:19], off offset:32
	global_load_dwordx4 v[94:97], v[18:19], off offset:64
	global_load_dwordx4 v[98:101], v[18:19], off offset:96
	v_lshrrev_b32_e32 v17, 3, v229
	v_bfe_u32 v18, v229, 2, 1
	v_and_or_b32 v22, v17, 2, v18
	v_lshrrev_b32_e32 v17, 1, v229
	v_and_b32_e32 v18, 3, v229
	v_or_b32_e32 v23, s19, v22
	v_and_or_b32 v198, v17, 4, v18
	v_lshl_add_u32 v18, v23, 3, s22
	v_ashrrev_i32_e32 v19, 31, v18
	v_lshl_add_u64 v[18:19], s[26:27], 0, v[18:19]
	v_or_b32_e32 v18, v18, v198
	v_lshlrev_b64 v[18:19], 7, v[18:19]
	v_lshl_add_u64 v[18:19], s[50:51], 0, v[18:19]
	v_lshl_add_u64 v[18:19], v[18:19], 0, v[20:21]
	global_load_dwordx4 v[110:113], v[18:19], off
	global_load_dwordx4 v[126:129], v[18:19], off offset:32
	global_load_dwordx4 v[130:133], v[18:19], off offset:64
	global_load_dwordx4 v[106:109], v[18:19], off offset:96
	v_mul_lo_u32 v17, v229, s31
	v_add_u32_e32 v17, 0, v17
	v_add_u32_e32 v17, 0x24000, v17
	ds_read_b128 v[102:105], v17
	ds_read_b128 v[114:117], v17 offset:16
	ds_read_b128 v[118:121], v17 offset:32
	ds_read_b128 v[122:125], v17 offset:48
	ds_read_b128 v[134:137], v17 offset:64
	ds_read_b128 v[138:141], v17 offset:80
	ds_read_b128 v[142:145], v17 offset:96
	ds_read_b128 v[146:149], v17 offset:112
	ds_read_b128 v[150:153], v17 offset:128
	s_waitcnt lgkmcnt(8)
	v_mad_u64_u32 v[18:19], s[0:1], v102, 3, 0
	v_lshlrev_b32_e32 v24, 3, v22
	v_or_b32_e32 v17, 0xffffffe4, v22
	v_or_b32_e32 v231, s21, v22
	v_mov_b32_e32 v22, v19
	v_or_b32_e32 v232, -16, v23
	v_mad_u64_u32 v[22:23], s[0:1], v103, 3, v[22:23]
	s_waitcnt lgkmcnt(7)
	v_sub_co_u32_e32 v18, vcc, v18, v114
	v_mov_b64_e32 v[156:157], v[84:85]
	s_nop 0
	v_subb_co_u32_e32 v19, vcc, v22, v115, vcc
	s_waitcnt lgkmcnt(5)
	v_lshl_add_u64 v[202:203], v[18:19], 0, v[122:123]
	v_mad_u64_u32 v[18:19], s[0:1], v104, 3, 0
	v_mov_b32_e32 v22, v19
	v_mad_u64_u32 v[22:23], s[0:1], v105, 3, v[22:23]
	v_sub_co_u32_e32 v18, vcc, v18, v116
	v_lshlrev_b32_e32 v190, 4, v230
	s_nop 0
	v_subb_co_u32_e32 v19, vcc, v22, v117, vcc
	v_add_u32_e32 v235, 2, v228
	v_lshl_add_u64 v[204:205], v[18:19], 0, v[124:125]
	v_mov_b32_e32 v18, 0
	s_lshl_b32 s23, s98, 6
	v_mov_b64_e32 v[154:155], v[82:83]
	v_lshl_add_u32 v200, v228, 4, 0
	v_add_u32_e32 v233, s93, v190
	v_add_u32_e32 v234, s21, v228
	v_add_u32_e32 v236, s21, v235
	v_subrev_u32_e32 v237, 26, v228
	s_mov_b32 s19, 10
	v_lshl_add_u32 v238, v228, 10, v214
	v_lshl_add_u64 v[206:207], s[50:51], 0, v[20:21]
	v_lshl_add_u64 v[208:209], s[52:53], 0, v[190:191]
	v_or3_b32 v239, v198, v24, s36
	s_mov_b32 s10, 0
	s_mov_b64 s[0:1], -1
	v_mov_b32_e32 v19, v18
	v_mov_b32_e32 v20, v18
	v_mov_b32_e32 v21, v18
	v_mov_b32_e32 v22, v18
	v_mov_b32_e32 v23, v18
	v_mov_b32_e32 v24, v18
	v_mov_b32_e32 v25, v18
	v_mov_b32_e32 v26, v18
	v_mov_b32_e32 v27, v18
	v_mov_b32_e32 v28, v18
	v_mov_b32_e32 v29, v18
	v_mov_b32_e32 v30, v18
	v_mov_b32_e32 v31, v18
	v_mov_b32_e32 v32, v18
	v_mov_b32_e32 v33, v18
	v_mov_b32_e32 v34, v18
	v_mov_b32_e32 v35, v18
	v_mov_b32_e32 v36, v18
	v_mov_b32_e32 v37, v18
	v_mov_b32_e32 v38, v18
	v_mov_b32_e32 v39, v18
	v_mov_b32_e32 v40, v18
	v_mov_b32_e32 v41, v18
	v_mov_b32_e32 v42, v18
	v_mov_b32_e32 v43, v18
	v_mov_b32_e32 v44, v18
	v_mov_b32_e32 v45, v18
	v_mov_b32_e32 v46, v18
	v_mov_b32_e32 v47, v18
	v_mov_b32_e32 v48, v18
	v_mov_b32_e32 v49, v18
	v_mov_b32_e32 v50, v18
	v_mov_b32_e32 v51, v18
	v_mov_b32_e32 v52, v18
	v_mov_b32_e32 v53, v18
	v_mov_b32_e32 v54, v18
	v_mov_b32_e32 v55, v18
	v_mov_b32_e32 v56, v18
	v_mov_b32_e32 v57, v18
	v_mov_b32_e32 v58, v18
	v_mov_b32_e32 v59, v18
	v_mov_b32_e32 v60, v18
	v_mov_b32_e32 v61, v18
	v_mov_b32_e32 v62, v18
	v_mov_b32_e32 v63, v18
	v_mov_b32_e32 v64, v18
	v_mov_b32_e32 v65, v18
	s_waitcnt vmcnt(4)
	v_mul_lo_u32 v245, v239, s71
	v_add_u32_e32 v245, v245, v200
	s_branch .LBB0_251

; __device__ __forceinline__ unsigned pk2(float lo, float hi) { f32x2 v = {lo, hi}; bf16x2_t b = __builtin_convertvector(v, bf16x2_t); return __builtin_bit_cast(unsigned, b); }
; __device__ __forceinline__ void attn_task(const AttnP& P, LAS unsigned char* lds, int b, int hd, int qq, int c, float shift, int lane_in) {
;     ...
;     const size_t tok = (size_t)b * SEQ + c + 16 * (iq0 + q);
;     if (h == 0) P.ssqA[tok * 8 + hd] = ss;
;     bf16_t* orow = P.MIX + tok * DM + hd * 64;
; #pragma unroll
;     for (int e4 = 0; e4 < 4; ++e4) {
;         const int d0 = 8 * e4 + 4 * h;
;         u32x2 w0, w1;
;         w0.x = pk2(o0[4 * e4], o0[4 * e4 + 1]); w0.y = pk2(o0[4 * e4 + 2], o0[4 * e4 + 3]);
;         w1.x = pk2(o1[4 * e4], o1[4 * e4 + 1]); w1.y = pk2(o1[4 * e4 + 2], o1[4 * e4 + 3]);
;         *(u32x2*)(orow + d0) = w0; *(u32x2*)(orow + 32 + d0) = w1;
;     }
; __device__ __forceinline__ void attn_unit(const AttnP& P, LAS unsigned char* lds, int b, int hd, int qq, int wave, int lane) {
;     ...
;     { const float mq = wave_max(fabsf(P.gq[lane])), mk = wave_max(fabsf(P.gk[lane])); shift = fminf(8.0f * mq * mk * 1.4426950408889634f, 64.0f); shift = shift > 30.0f ? shift : 0.f; }
;     {
;         u32x4 kr[8], vr[8];
; #pragma unroll
;         for (int j = 0; j < 8; ++j) { const int chunk = tid + 512 * j, row = chunk >> 3, piece = chunk & 7, cls = row >> 5, il = row & 31;
;             kr[j] = *(const u32x4*)(P.K + ((size_t)(hb * 16 + cls) * 128 + 32 * qq + il) * 64 + piece * 8); }
; #pragma unroll
;         for (int j = 0; j < 8; ++j) { const int chunk = tid + 512 * j, cls = chunk >> 8, within = chunk & 255;
;             vr[j] = *(const u32x4*)(P.Vt + ((size_t)(hb * 16 + cls) * 16 + 4 * qq) * 512 + within * 8); }
;         __syncthreads();
.LBB0_329:
	s_or_b64 exec, exec, s[0:1]
	v_readlane_b32 s0, v243, 20
	v_lshlrev_b64 v[34:35], 11, v[190:191]
	v_readlane_b32 s1, v243, 21
	s_lshl_b32 s58, s23, 1
	v_lshlrev_b32_e32 v36, 2, v228
	v_lshl_add_u64 v[34:35], s[0:1], 0, v[34:35]
	v_lshl_add_u64 v[34:35], v[34:35], 0, s[58:59]
	v_ashrrev_i32_e32 v37, 31, v36
	v_cvt_pk_bf16_f32 v128, v4, v5
	v_cvt_pk_bf16_f32 v129, v10, v11
	v_cvt_pk_bf16_f32 v136, v2, v3
	v_cvt_pk_bf16_f32 v137, v6, v7
	v_lshl_add_u64 v[6:7], v[36:37], 1, v[34:35]
	v_bfe_u32 v144, v0, 5, 1
	v_lshlrev_b32_e32 v144, 3, v144
	v_mov_b32_e32 v145, 0
	v_lshl_add_u64 v[146:147], v[6:7], 0, v[144:145]
	v_cvt_pk_bf16_f32 v130, v12, v13
	v_cvt_pk_bf16_f32 v131, v16, v17
	v_cvt_pk_bf16_f32 v138, v8, v9
	v_cvt_pk_bf16_f32 v139, v14, v15
	s_nop 1
	v_permlane32_swap_b32_e32 v128, v130
	v_permlane32_swap_b32_e32 v129, v131
	global_store_dwordx4 v[146:147], v[128:131], off
	s_nop 1
	v_permlane32_swap_b32_e32 v136, v138
	v_permlane32_swap_b32_e32 v137, v139
	global_store_dwordx4 v[146:147], v[136:139], off offset:64
	v_cvt_pk_bf16_f32 v132, v20, v21
	v_cvt_pk_bf16_f32 v133, v24, v25
	v_cvt_pk_bf16_f32 v140, v18, v19
	v_cvt_pk_bf16_f32 v141, v22, v23
	v_cvt_pk_bf16_f32 v134, v28, v29
	v_cvt_pk_bf16_f32 v135, v32, v33
	v_mov_b32_e32 v1, v0
	v_cvt_pk_bf16_f32 v142, v26, v27
	v_cvt_pk_bf16_f32 v143, v30, v31
	s_nop 1
	v_permlane32_swap_b32_e32 v132, v134
	v_permlane32_swap_b32_e32 v133, v135
	global_store_dwordx4 v[146:147], v[132:135], off offset:32
	s_nop 1
	v_permlane32_swap_b32_e32 v140, v142
	v_permlane32_swap_b32_e32 v141, v143
	global_store_dwordx4 v[146:147], v[140:143], off offset:96
	s_lshl_b32 s0, s12, 12
	v_add_u32_e32 v70, 0x200, v1
	v_ashrrev_i32_e32 v2, 8, v1
	v_ashrrev_i32_e32 v4, 8, v70
	v_lshlrev_b32_e32 v67, 4, v1
	v_add_u32_e32 v2, s99, v2
	v_add_u32_e32 v4, s99, v4
	v_add_u32_e32 v71, 0x400, v1
	v_add_u32_e32 v72, 0x600, v1
	v_and_b32_e32 v190, 0x70, v67
	v_ashrrev_i32_e32 v3, 31, v2
	v_ashrrev_i32_e32 v5, 31, v4
	v_ashrrev_i32_e32 v10, 8, v71
	v_ashrrev_i32_e32 v12, 8, v72
	v_lshl_add_u64 v[26:27], s[50:51], 0, v[190:191]
	v_lshlrev_b64 v[34:35], 14, v[2:3]
	v_and_b32_e32 v2, 0xf80, v67
	v_lshlrev_b64 v[36:37], 14, v[4:5]
	v_add_u32_e32 v10, s99, v10
	v_add_u32_e32 v12, s99, v12
	v_add_u32_e32 v73, 0x800, v1
	v_add_u32_e32 v74, 0xa00, v1
	v_or_b32_e32 v28, s0, v2
	v_mov_b32_e32 v29, v191
	v_lshl_add_u64 v[2:3], v[26:27], 0, v[34:35]
	v_lshl_add_u64 v[4:5], v[26:27], 0, v[36:37]
	v_ashrrev_i32_e32 v11, 31, v10
	v_ashrrev_i32_e32 v13, 31, v12
	v_ashrrev_i32_e32 v18, 8, v73
	v_ashrrev_i32_e32 v20, 8, v74
	v_lshl_add_u64 v[2:3], v[2:3], 0, v[28:29]
	v_lshl_add_u64 v[6:7], v[4:5], 0, v[28:29]
	v_lshlrev_b64 v[42:43], 14, v[10:11]
	v_lshlrev_b64 v[44:45], 14, v[12:13]
	v_add_u32_e32 v18, s99, v18
	v_add_u32_e32 v20, s99, v20
	v_add_u32_e32 v75, 0xc00, v1
	v_add_u32_e32 v76, 0xe00, v1
	global_load_dwordx4 v[2:5], v[2:3], off
	s_nop 0
	global_load_dwordx4 v[6:9], v[6:7], off
	v_lshl_add_u64 v[10:11], v[26:27], 0, v[42:43]
	v_lshl_add_u64 v[12:13], v[26:27], 0, v[44:45]
	v_ashrrev_i32_e32 v19, 31, v18
	v_ashrrev_i32_e32 v21, 31, v20
	v_ashrrev_i32_e32 v30, 8, v75
	v_ashrrev_i32_e32 v32, 8, v76
	v_lshl_add_u64 v[10:11], v[10:11], 0, v[28:29]
	v_lshl_add_u64 v[14:15], v[12:13], 0, v[28:29]
	v_lshlrev_b64 v[50:51], 14, v[18:19]
	v_lshlrev_b64 v[52:53], 14, v[20:21]
	v_add_u32_e32 v30, s99, v30
	v_add_u32_e32 v32, s99, v32
	global_load_dwordx4 v[10:13], v[10:11], off
	s_nop 0
	global_load_dwordx4 v[14:17], v[14:15], off
	v_lshl_add_u64 v[18:19], v[26:27], 0, v[50:51]
	v_lshl_add_u64 v[20:21], v[26:27], 0, v[52:53]
	v_ashrrev_i32_e32 v31, 31, v30
	v_ashrrev_i32_e32 v33, 31, v32
	v_lshl_add_u64 v[18:19], v[18:19], 0, v[28:29]
	v_lshl_add_u64 v[22:23], v[20:21], 0, v[28:29]
	v_lshlrev_b64 v[58:59], 14, v[30:31]
	v_lshlrev_b64 v[60:61], 14, v[32:33]
	s_add_u32 s0, s52, s0
	global_load_dwordx4 v[18:21], v[18:19], off
	s_nop 0
	global_load_dwordx4 v[22:25], v[22:23], off
	v_lshl_add_u64 v[30:31], v[26:27], 0, v[58:59]
	v_lshl_add_u64 v[26:27], v[26:27], 0, v[60:61]
	s_addc_u32 s1, s53, 0
	v_and_b32_e32 v38, 0xff0, v67
	v_mov_b32_e32 v39, v191
	v_lshl_add_u64 v[30:31], v[30:31], 0, v[28:29]
	v_lshl_add_u64 v[32:33], v[26:27], 0, v[28:29]
	v_lshl_add_u64 v[62:63], s[0:1], 0, v[38:39]
	global_load_dwordx4 v[26:29], v[30:31], off
	s_nop 0
	global_load_dwordx4 v[30:33], v[32:33], off
	v_lshl_add_u64 v[34:35], v[62:63], 0, v[34:35]
	v_lshl_add_u64 v[38:39], v[62:63], 0, v[36:37]
	v_lshl_add_u64 v[42:43], v[62:63], 0, v[42:43]
	v_lshl_add_u64 v[46:47], v[62:63], 0, v[44:45]
	v_lshl_add_u64 v[50:51], v[62:63], 0, v[50:51]
	v_lshl_add_u64 v[54:55], v[62:63], 0, v[52:53]
	global_load_dwordx4 v[34:37], v[34:35], off
	s_nop 0
	global_load_dwordx4 v[38:41], v[38:39], off
	s_nop 0
	global_load_dwordx4 v[42:45], v[42:43], off
	s_nop 0
	global_load_dwordx4 v[46:49], v[46:47], off
	s_nop 0
	global_load_dwordx4 v[50:53], v[50:51], off
	s_nop 0
	global_load_dwordx4 v[54:57], v[54:55], off
	v_lshl_add_u64 v[58:59], v[62:63], 0, v[58:59]
	v_lshl_add_u64 v[62:63], v[62:63], 0, v[60:61]
	global_load_dwordx4 v[58:61], v[58:59], off
	s_nop 0
	global_load_dwordx4 v[62:65], v[62:63], off
	s_nop 0
	global_load_dword v77, v[192:193], off
	global_load_dword v78, v[194:195], off
	v_add_u32_e32 v66, 0, v190
	v_lshrrev_b32_e32 v1, 3, v1
	v_mad_u64_u32 v[68:69], s[0:1], v1, s71, v[66:67]
	v_lshrrev_b32_e32 v1, 3, v70
	s_barrier
; #define LAS __attribute__((address_space(3)))
; __device__ __forceinline__ void attn_unit(const AttnP& P, LAS unsigned char* lds, int b, int hd, int qq, int wave, int lane) {
;     ...
;     { const float mq = wave_max(fabsf(P.gq[lane])), mk = wave_max(fabsf(P.gk[lane])); shift = fminf(8.0f * mq * mk * 1.4426950408889634f, 64.0f); shift = shift > 30.0f ? shift : 0.f; }
;     {
;         u32x4 kr[8], vr[8];
; #pragma unroll
;         for (int j = 0; j < 8; ++j) { const int chunk = tid + 512 * j, row = chunk >> 3, piece = chunk & 7, cls = row >> 5, il = row & 31;
;             kr[j] = *(const u32x4*)(P.K + ((size_t)(hb * 16 + cls) * 128 + 32 * qq + il) * 64 + piece * 8); }
; #pragma unroll
;         for (int j = 0; j < 8; ++j) { const int chunk = tid + 512 * j, cls = chunk >> 8, within = chunk & 255;
;             vr[j] = *(const u32x4*)(P.Vt + ((size_t)(hb * 16 + cls) * 16 + 4 * qq) * 512 + within * 8); }
;         __syncthreads();
; #pragma unroll
;         for (int j = 0; j < 8; ++j) { const int chunk = tid + 512 * j, row = chunk >> 3, piece = chunk & 7;
;             *(LAS u32x4*)(lds + LDS_KC + row * KC_PITCH + piece * 16) = kr[j]; }
; #pragma unroll
;         for (int j = 0; j < 8; ++j) { const int chunk = tid + 512 * j; *(LAS u32x4*)(lds + LDS_VC + chunk * 16) = vr[j]; }
;     }
;     __syncthreads();
	v_mov_b32_e32 v228, v201
	s_lshl_b32 s38, s12, 5
	s_cmp_lg_u32 s12, 0
	s_cselect_b64 s[60:61], -1, 0
	s_cmp_eq_u32 s12, 0
	s_cselect_b64 s[28:29], -1, 0
	s_and_b64 vcc, exec, s[60:61]
	s_waitcnt vmcnt(17)
	ds_write_b128 v68, v[2:5]
	v_mad_u64_u32 v[2:3], s[0:1], v1, s71, v[66:67]
	v_lshrrev_b32_e32 v1, 3, v71
	s_waitcnt vmcnt(16)
	ds_write_b128 v2, v[6:9]
	v_mad_u64_u32 v[2:3], s[0:1], v1, s71, v[66:67]
	v_lshrrev_b32_e32 v1, 3, v72
	s_waitcnt vmcnt(15)
	ds_write_b128 v2, v[10:13]
	v_mad_u64_u32 v[2:3], s[0:1], v1, s71, v[66:67]
	v_lshrrev_b32_e32 v1, 3, v73
	s_waitcnt vmcnt(14)
	ds_write_b128 v2, v[14:17]
	v_mad_u64_u32 v[2:3], s[0:1], v1, s71, v[66:67]
	v_lshrrev_b32_e32 v1, 3, v74
	s_waitcnt vmcnt(13)
	ds_write_b128 v2, v[18:21]
	v_mad_u64_u32 v[2:3], s[0:1], v1, s71, v[66:67]
	v_lshrrev_b32_e32 v1, 3, v75
	s_waitcnt vmcnt(12)
	ds_write_b128 v2, v[22:25]
	v_mad_u64_u32 v[2:3], s[0:1], v1, s71, v[66:67]
	v_lshrrev_b32_e32 v1, 3, v76
	s_waitcnt vmcnt(11)
	ds_write_b128 v2, v[26:29]
	v_mad_u64_u32 v[2:3], s[0:1], v1, s71, v[66:67]
	v_add_u32_e32 v1, 0, v67
	v_add_u32_e32 v1, 0x14000, v1
	s_waitcnt vmcnt(10)
	ds_write_b128 v2, v[30:33]
	s_waitcnt vmcnt(9)
	ds_write_b128 v1, v[34:37]
	s_waitcnt vmcnt(8)
	ds_write_b128 v1, v[38:41] offset:8192
	s_waitcnt vmcnt(7)
	ds_write_b128 v1, v[42:45] offset:16384
	s_waitcnt vmcnt(6)
	ds_write_b128 v1, v[46:49] offset:24576
	s_waitcnt vmcnt(5)
	ds_write_b128 v1, v[50:53] offset:32768
	s_waitcnt vmcnt(4)
	ds_write_b128 v1, v[54:57] offset:40960
	s_waitcnt vmcnt(3)
	ds_write_b128 v1, v[58:61] offset:49152
	s_waitcnt vmcnt(2)
	ds_write_b128 v1, v[62:65] offset:57344
	s_waitcnt lgkmcnt(0)
	s_barrier
	v_mov_b32_e32 v3, s7
	v_and_b32_e32 v229, 31, v228
	v_or_b32_e32 v1, s6, v229
	v_ashrrev_i32_e32 v17, 5, v228
	v_or_b32_e32 v2, s38, v1
	v_lshlrev_b64 v[2:3], 7, v[2:3]
	v_lshlrev_b32_e32 v4, 3, v17
	v_lshl_add_u64 v[2:3], s[46:47], 0, v[2:3]
	v_ashrrev_i32_e32 v5, 31, v4
	v_lshl_add_u64 v[2:3], v[4:5], 1, v[2:3]
	global_load_dwordx4 v[86:89], v[2:3], off
	global_load_dwordx4 v[90:93], v[2:3], off offset:32
	global_load_dwordx4 v[94:97], v[2:3], off offset:64
	global_load_dwordx4 v[98:101], v[2:3], off offset:96
	s_waitcnt vmcnt(5)
	v_and_b32_e32 v1, 0x7fffffff, v77
	ds_bpermute_b32 v1, v225, v1
	s_waitcnt vmcnt(4)
	v_and_b32_e32 v2, 0x7fffffff, v78
	ds_bpermute_b32 v2, v225, v2
	v_max_f32_e64 v3, |v77|, |v77|
	v_max_f32_e64 v6, |v78|, |v78|
	s_waitcnt lgkmcnt(1)
	v_max_f32_e32 v1, v1, v1
	v_max_f32_e32 v1, v3, v1
	s_waitcnt lgkmcnt(0)
	v_max_f32_e32 v2, v2, v2
	ds_bpermute_b32 v3, v224, v1
	v_max_f32_e32 v2, v6, v2
	ds_bpermute_b32 v6, v224, v2
	v_and_b32_e32 v9, 3, v228
	s_mov_b64 s[0:1], -1
	s_waitcnt lgkmcnt(1)
	v_max_f32_e32 v3, v3, v3
	v_max_f32_e32 v1, v1, v3
	s_waitcnt lgkmcnt(0)
	v_max_f32_e32 v6, v6, v6
	ds_bpermute_b32 v3, v223, v1
	v_max_f32_e32 v2, v2, v6
	ds_bpermute_b32 v6, v223, v2
	s_waitcnt lgkmcnt(1)
	v_max_f32_e32 v3, v3, v3
	v_max_f32_e32 v1, v1, v3
	s_waitcnt lgkmcnt(0)
	v_max_f32_e32 v6, v6, v6
	ds_bpermute_b32 v3, v199, v1
	v_max_f32_e32 v2, v2, v6
	ds_bpermute_b32 v6, v199, v2
	s_waitcnt lgkmcnt(1)
	v_max_f32_e32 v3, v3, v3
	v_max_f32_e32 v1, v1, v3
	s_waitcnt lgkmcnt(0)
	v_max_f32_e32 v6, v6, v6
	ds_bpermute_b32 v3, v226, v1
	v_max_f32_e32 v6, v2, v6
	ds_bpermute_b32 v8, v226, v6
	s_waitcnt lgkmcnt(1)
	v_max_f32_e32 v2, v3, v3
	v_max_f32_e32 v2, v1, v2
	s_waitcnt lgkmcnt(0)
	v_max_f32_e32 v1, v8, v8
	v_max_f32_e32 v6, v6, v1
	ds_bpermute_b32 v7, v227, v2
	ds_bpermute_b32 v8, v227, v6
	v_lshrrev_b32_e32 v1, 3, v228
	v_bfe_u32 v3, v228, 2, 1
	v_and_or_b32 v1, v1, 2, v3
	v_lshrrev_b32_e32 v3, 1, v228
	v_and_or_b32 v190, v3, 4, v9
	v_lshlrev_b32_e32 v9, 3, v1
	v_mov_b64_e32 v[198:199], v[190:191]
	s_cbranch_vccnz .LBB0_331
	v_lshlrev_b32_e32 v3, 3, v1
	s_mov_b64 s[0:1], 0
	v_mov_b64_e32 v[198:199], v[190:191]

; __device__ __forceinline__ unsigned pk2(float lo, float hi) { f32x2 v = {lo, hi}; bf16x2_t b = __builtin_convertvector(v, bf16x2_t); return __builtin_bit_cast(unsigned, b); }
; __device__ __forceinline__ int next_tile(int tt, int R0) { while (tt < 26 && !tile_valid(tt, R0)) ++tt; return tt; }
; __device__ __forceinline__ void attn_task(const AttnP& P, LAS unsigned char* lds, int b, int hd, int qq, int c, float shift, int lane_in) {
;     ...
;     const int hb = b * 8 + hd, q = lane & 31, h = lane >> 5, R0 = 4 * qq, iq0 = 32 * qq;
;     bf16x8 qf[4];
;     { const bf16_t* qp = P.Q + ((size_t)(hb * 16 + c) * 128 + iq0 + q) * 64 + 8 * h;
; #pragma unroll
;       for (int kk = 0; kk < 4; ++kk) qf[kk] = *(const bf16x8*)(qp + 16 * kk); }
;     bf16x8 gk[4];
;     int gi = next_tile(0, R0);
;     if (gi < 10) attn_load_k(P, lds, hb, gi, c, R0, lane, gk);
;     ...
;     const size_t tok = (size_t)b * SEQ + c + 16 * (iq0 + q);
;     if (h == 0) P.ssqA[tok * 8 + hd] = ss;
;     bf16_t* orow = P.MIX + tok * DM + hd * 64;
; #pragma unroll
;     for (int e4 = 0; e4 < 4; ++e4) {
;         const int d0 = 8 * e4 + 4 * h;
;         u32x2 w0, w1;
;         w0.x = pk2(o0[4 * e4], o0[4 * e4 + 1]); w0.y = pk2(o0[4 * e4 + 2], o0[4 * e4 + 3]);
;         w1.x = pk2(o1[4 * e4], o1[4 * e4 + 1]); w1.y = pk2(o1[4 * e4 + 2], o1[4 * e4 + 3]);
;         *(u32x2*)(orow + d0) = w0; *(u32x2*)(orow + 32 + d0) = w1;
;     }
.LBB0_432:
	s_or_b64 exec, exec, s[0:1]
	v_readlane_b32 s0, v243, 20
	v_lshlrev_b64 v[48:49], 11, v[190:191]
	v_readlane_b32 s1, v243, 21
	v_lshlrev_b32_e32 v52, 2, v17
	v_ashrrev_i32_e32 v53, 31, v52
	v_lshl_add_u64 v[48:49], s[0:1], 0, v[48:49]
	v_lshl_add_u64 v[48:49], v[48:49], 0, s[58:59]
	v_cvt_pk_bf16_f32 v128, v50, v51
	v_cvt_pk_bf16_f32 v129, v34, v35
	v_cvt_pk_bf16_f32 v136, v18, v19
	v_cvt_pk_bf16_f32 v137, v20, v21
	v_lshl_add_u64 v[20:21], v[52:53], 1, v[48:49]
	v_bfe_u32 v144, v0, 5, 1
	v_lshlrev_b32_e32 v144, 3, v144
	v_mov_b32_e32 v145, 0
	v_lshl_add_u64 v[146:147], v[20:21], 0, v[144:145]
	v_cvt_pk_bf16_f32 v130, v36, v37
	v_cvt_pk_bf16_f32 v131, v38, v39
	v_cvt_pk_bf16_f32 v138, v22, v23
	v_cvt_pk_bf16_f32 v139, v24, v25
	s_nop 1
	v_permlane32_swap_b32_e32 v128, v130
	v_permlane32_swap_b32_e32 v129, v131
	global_store_dwordx4 v[146:147], v[128:131], off
	s_nop 1
	v_permlane32_swap_b32_e32 v136, v138
	v_permlane32_swap_b32_e32 v137, v139
	global_store_dwordx4 v[146:147], v[136:139], off offset:64
	v_cvt_pk_bf16_f32 v132, v40, v41
	v_cvt_pk_bf16_f32 v133, v42, v43
	v_cvt_pk_bf16_f32 v140, v26, v27
	v_cvt_pk_bf16_f32 v141, v28, v29
	v_cvt_pk_bf16_f32 v134, v44, v45
	v_cvt_pk_bf16_f32 v135, v46, v47
	v_mov_b32_e32 v224, v201
	v_cvt_pk_bf16_f32 v142, v30, v31
	v_cvt_pk_bf16_f32 v143, v32, v33
	s_nop 1
	v_permlane32_swap_b32_e32 v132, v134
	v_permlane32_swap_b32_e32 v133, v135
	global_store_dwordx4 v[146:147], v[132:135], off offset:32
	s_nop 1
	v_permlane32_swap_b32_e32 v140, v142
	v_permlane32_swap_b32_e32 v141, v143
	global_store_dwordx4 v[146:147], v[140:143], off offset:96
	v_mov_b32_e32 v19, s27
	v_and_b32_e32 v225, 31, v224
	v_or_b32_e32 v17, s26, v225
	v_or_b32_e32 v18, s38, v17
	v_ashrrev_i32_e32 v223, 5, v224
	v_lshlrev_b64 v[18:19], 7, v[18:19]
	v_lshl_add_u64 v[20:21], s[46:47], 0, v[18:19]
	v_lshlrev_b32_e32 v18, 3, v223
	v_ashrrev_i32_e32 v19, 31, v18
	v_lshl_add_u64 v[20:21], v[18:19], 1, v[20:21]
	global_load_dwordx4 v[86:89], v[20:21], off
	global_load_dwordx4 v[90:93], v[20:21], off offset:32
	global_load_dwordx4 v[94:97], v[20:21], off offset:64
	global_load_dwordx4 v[98:101], v[20:21], off offset:96
	v_lshrrev_b32_e32 v17, 3, v224
	v_bfe_u32 v20, v224, 2, 1
	v_and_or_b32 v20, v17, 2, v20
	v_lshrrev_b32_e32 v17, 1, v224
	v_and_b32_e32 v21, 3, v224
	v_and_or_b32 v190, v17, 4, v21
	s_mov_b64 s[0:1], -1
	s_andn2_b64 vcc, exec, s[28:29]
	v_lshlrev_b32_e32 v17, 3, v20
	v_mov_b64_e32 v[198:199], v[190:191]
	s_cbranch_vccnz .LBB0_434
	v_lshlrev_b32_e32 v21, 3, v20
	s_mov_b64 s[0:1], 0
	v_mov_b64_e32 v[198:199], v[190:191]
